# in-proj epilogues: 1/rms loads batched at top, no per-block vmcnt(0) drains
# speedup vs baseline: 1.0296x; 1.0101x over previous
.LBB0_165:
	v_lshl_add_u32 v144, s52, 8, v140
	v_ashrrev_i32_e32 v145, 31, v144
	v_lshl_add_u64 v[138:139], v[144:145], 2, s[80:81]
	global_load_dword v146, v[138:139], off
	global_load_dword v163, v[138:139], off offset:64
	global_load_dword v164, v[138:139], off offset:128
	global_load_dword v165, v[138:139], off offset:192
	global_load_dword v166, v[138:139], off offset:512
	global_load_dword v167, v[138:139], off offset:576
	global_load_dword v168, v[138:139], off offset:640
	global_load_dword v169, v[138:139], off offset:704
	v_lshl_or_b32 v145, s51, 9, v142
	s_mov_b32 s6, s82
	s_mov_b32 s7, s83
	v_lshl_add_u32 v148, v144, 13, v145
	s_andn2_b64 vcc, exec, s[34:35]
	s_waitcnt vmcnt(0)
	v_pk_mul_f32 v[126:127], v[126:127], v[146:147] op_sel_hi:[1,0]
	v_pk_mul_f32 v[124:125], v[124:125], v[146:147] op_sel_hi:[1,0]
	v_pk_mul_f32 v[122:123], v[122:123], v[146:147] op_sel_hi:[1,0]
	v_pk_mul_f32 v[120:121], v[120:121], v[146:147] op_sel_hi:[1,0]
	v_pk_mul_f32 v[118:119], v[118:119], v[146:147] op_sel_hi:[1,0]
	v_pk_mul_f32 v[116:117], v[116:117], v[146:147] op_sel_hi:[1,0]
	v_pk_mul_f32 v[144:145], v[114:115], v[146:147] op_sel_hi:[1,0]
	v_pk_mul_f32 v[146:147], v[112:113], v[146:147] op_sel_hi:[1,0]
	v_cvt_pk_bf16_f32 v112, v124, v125
	v_cvt_pk_bf16_f32 v113, v126, v127
	v_cvt_pk_bf16_f32 v114, v120, v121
	v_cvt_pk_bf16_f32 v115, v122, v123
	buffer_store_dwordx4 v[112:115], v148, s[4:7], 0 offen sc1
	s_nop 1
	v_cvt_pk_bf16_f32 v112, v116, v117
	v_cvt_pk_bf16_f32 v113, v118, v119
	v_cvt_pk_bf16_f32 v114, v146, v147
	v_cvt_pk_bf16_f32 v115, v144, v145
	buffer_store_dwordx4 v[112:115], v148, s[4:7], 0 offen offset:256 sc1
	s_nop 1
	v_mov_b32_e32 v112, v163
	v_add_u32_e32 v116, 0x20000, v148
	v_pk_mul_f32 v[110:111], v[110:111], v[112:113] op_sel_hi:[1,0]
	v_pk_mul_f32 v[108:109], v[108:109], v[112:113] op_sel_hi:[1,0]
	v_pk_mul_f32 v[106:107], v[106:107], v[112:113] op_sel_hi:[1,0]
	v_pk_mul_f32 v[104:105], v[104:105], v[112:113] op_sel_hi:[1,0]
	v_pk_mul_f32 v[102:103], v[102:103], v[112:113] op_sel_hi:[1,0]
	v_pk_mul_f32 v[100:101], v[100:101], v[112:113] op_sel_hi:[1,0]
	v_pk_mul_f32 v[114:115], v[98:99], v[112:113] op_sel_hi:[1,0]
	v_pk_mul_f32 v[112:113], v[96:97], v[112:113] op_sel_hi:[1,0]
	v_cvt_pk_bf16_f32 v96, v108, v109
	v_cvt_pk_bf16_f32 v97, v110, v111
	v_cvt_pk_bf16_f32 v98, v104, v105
	v_cvt_pk_bf16_f32 v99, v106, v107
	buffer_store_dwordx4 v[96:99], v116, s[4:7], 0 offen sc1
	s_nop 1
	v_cvt_pk_bf16_f32 v96, v100, v101
	v_cvt_pk_bf16_f32 v97, v102, v103
	v_cvt_pk_bf16_f32 v98, v112, v113
	v_cvt_pk_bf16_f32 v99, v114, v115
	buffer_store_dwordx4 v[96:99], v116, s[4:7], 0 offen offset:256 sc1
	s_nop 1
	v_mov_b32_e32 v96, v164
	v_add_u32_e32 v100, 0x40000, v148
	v_pk_mul_f32 v[94:95], v[94:95], v[96:97] op_sel_hi:[1,0]
	v_pk_mul_f32 v[92:93], v[92:93], v[96:97] op_sel_hi:[1,0]
	v_pk_mul_f32 v[90:91], v[90:91], v[96:97] op_sel_hi:[1,0]
	v_pk_mul_f32 v[88:89], v[88:89], v[96:97] op_sel_hi:[1,0]
	v_pk_mul_f32 v[86:87], v[86:87], v[96:97] op_sel_hi:[1,0]
	v_pk_mul_f32 v[84:85], v[84:85], v[96:97] op_sel_hi:[1,0]
	v_pk_mul_f32 v[98:99], v[82:83], v[96:97] op_sel_hi:[1,0]
	v_pk_mul_f32 v[96:97], v[80:81], v[96:97] op_sel_hi:[1,0]
	v_cvt_pk_bf16_f32 v80, v92, v93
	v_cvt_pk_bf16_f32 v81, v94, v95
	v_cvt_pk_bf16_f32 v82, v88, v89
	v_cvt_pk_bf16_f32 v83, v90, v91
	buffer_store_dwordx4 v[80:83], v100, s[4:7], 0 offen sc1
	s_nop 1
	v_cvt_pk_bf16_f32 v80, v84, v85
	v_cvt_pk_bf16_f32 v81, v86, v87
	v_cvt_pk_bf16_f32 v82, v96, v97
	v_cvt_pk_bf16_f32 v83, v98, v99
	buffer_store_dwordx4 v[80:83], v100, s[4:7], 0 offen offset:256 sc1
	s_nop 1
	v_mov_b32_e32 v80, v165
	v_add_u32_e32 v84, 0x60000, v148
	v_pk_mul_f32 v[78:79], v[78:79], v[80:81] op_sel_hi:[1,0]
	v_pk_mul_f32 v[76:77], v[76:77], v[80:81] op_sel_hi:[1,0]
	v_pk_mul_f32 v[74:75], v[74:75], v[80:81] op_sel_hi:[1,0]
	v_pk_mul_f32 v[72:73], v[72:73], v[80:81] op_sel_hi:[1,0]
	v_pk_mul_f32 v[70:71], v[70:71], v[80:81] op_sel_hi:[1,0]
	v_pk_mul_f32 v[68:69], v[68:69], v[80:81] op_sel_hi:[1,0]
	v_pk_mul_f32 v[82:83], v[66:67], v[80:81] op_sel_hi:[1,0]
	v_pk_mul_f32 v[80:81], v[64:65], v[80:81] op_sel_hi:[1,0]
	v_cvt_pk_bf16_f32 v64, v76, v77
	v_cvt_pk_bf16_f32 v65, v78, v79
	v_cvt_pk_bf16_f32 v66, v72, v73
	v_cvt_pk_bf16_f32 v67, v74, v75
	buffer_store_dwordx4 v[64:67], v84, s[4:7], 0 offen sc1
	s_nop 1
	v_cvt_pk_bf16_f32 v64, v68, v69
	v_cvt_pk_bf16_f32 v65, v70, v71
	v_cvt_pk_bf16_f32 v66, v80, v81
	v_cvt_pk_bf16_f32 v67, v82, v83
	buffer_store_dwordx4 v[64:67], v84, s[4:7], 0 offen offset:256 sc1
	s_nop 1
	v_mov_b32_e32 v64, v166
	v_add_u32_e32 v68, 0x100000, v148
	v_pk_mul_f32 v[62:63], v[62:63], v[64:65] op_sel_hi:[1,0]
	v_pk_mul_f32 v[60:61], v[60:61], v[64:65] op_sel_hi:[1,0]
	v_pk_mul_f32 v[58:59], v[58:59], v[64:65] op_sel_hi:[1,0]
	v_pk_mul_f32 v[56:57], v[56:57], v[64:65] op_sel_hi:[1,0]
	v_pk_mul_f32 v[54:55], v[54:55], v[64:65] op_sel_hi:[1,0]
	v_pk_mul_f32 v[52:53], v[52:53], v[64:65] op_sel_hi:[1,0]
	v_pk_mul_f32 v[66:67], v[50:51], v[64:65] op_sel_hi:[1,0]
	v_pk_mul_f32 v[64:65], v[48:49], v[64:65] op_sel_hi:[1,0]
	v_cvt_pk_bf16_f32 v48, v60, v61
	v_cvt_pk_bf16_f32 v49, v62, v63
	v_cvt_pk_bf16_f32 v50, v56, v57
	v_cvt_pk_bf16_f32 v51, v58, v59
	buffer_store_dwordx4 v[48:51], v68, s[4:7], 0 offen sc1
	s_nop 1
	v_cvt_pk_bf16_f32 v48, v52, v53
	v_cvt_pk_bf16_f32 v49, v54, v55
	v_cvt_pk_bf16_f32 v50, v64, v65
	v_cvt_pk_bf16_f32 v51, v66, v67
	buffer_store_dwordx4 v[48:51], v68, s[4:7], 0 offen offset:256 sc1
	s_nop 1
	v_mov_b32_e32 v48, v167
	v_add_u32_e32 v52, 0x120000, v148
	v_pk_mul_f32 v[46:47], v[46:47], v[48:49] op_sel_hi:[1,0]
	v_pk_mul_f32 v[44:45], v[44:45], v[48:49] op_sel_hi:[1,0]
	v_pk_mul_f32 v[42:43], v[42:43], v[48:49] op_sel_hi:[1,0]
	v_pk_mul_f32 v[40:41], v[40:41], v[48:49] op_sel_hi:[1,0]
	v_pk_mul_f32 v[38:39], v[38:39], v[48:49] op_sel_hi:[1,0]
	v_pk_mul_f32 v[36:37], v[36:37], v[48:49] op_sel_hi:[1,0]
	v_pk_mul_f32 v[50:51], v[34:35], v[48:49] op_sel_hi:[1,0]
	v_pk_mul_f32 v[48:49], v[32:33], v[48:49] op_sel_hi:[1,0]
	v_cvt_pk_bf16_f32 v32, v44, v45
	v_cvt_pk_bf16_f32 v33, v46, v47
	v_cvt_pk_bf16_f32 v34, v40, v41
	v_cvt_pk_bf16_f32 v35, v42, v43
	buffer_store_dwordx4 v[32:35], v52, s[4:7], 0 offen sc1
	s_nop 1
	v_cvt_pk_bf16_f32 v32, v36, v37
	v_cvt_pk_bf16_f32 v33, v38, v39
	v_cvt_pk_bf16_f32 v34, v48, v49
	v_cvt_pk_bf16_f32 v35, v50, v51
	buffer_store_dwordx4 v[32:35], v52, s[4:7], 0 offen offset:256 sc1
	s_nop 1
	v_mov_b32_e32 v32, v168
	v_add_u32_e32 v36, 0x140000, v148
	v_pk_mul_f32 v[30:31], v[30:31], v[32:33] op_sel_hi:[1,0]
	v_pk_mul_f32 v[28:29], v[28:29], v[32:33] op_sel_hi:[1,0]
	v_pk_mul_f32 v[26:27], v[26:27], v[32:33] op_sel_hi:[1,0]
	v_pk_mul_f32 v[24:25], v[24:25], v[32:33] op_sel_hi:[1,0]
	v_pk_mul_f32 v[22:23], v[22:23], v[32:33] op_sel_hi:[1,0]
	v_pk_mul_f32 v[20:21], v[20:21], v[32:33] op_sel_hi:[1,0]
	v_pk_mul_f32 v[34:35], v[18:19], v[32:33] op_sel_hi:[1,0]
	v_pk_mul_f32 v[32:33], v[16:17], v[32:33] op_sel_hi:[1,0]
	v_cvt_pk_bf16_f32 v16, v28, v29
	v_cvt_pk_bf16_f32 v17, v30, v31
	v_cvt_pk_bf16_f32 v18, v24, v25
	v_cvt_pk_bf16_f32 v19, v26, v27
	buffer_store_dwordx4 v[16:19], v36, s[4:7], 0 offen sc1
	s_nop 1
	v_cvt_pk_bf16_f32 v16, v20, v21
	v_cvt_pk_bf16_f32 v17, v22, v23
	v_cvt_pk_bf16_f32 v18, v32, v33
	v_cvt_pk_bf16_f32 v19, v34, v35
	buffer_store_dwordx4 v[16:19], v36, s[4:7], 0 offen offset:256 sc1
	s_nop 1
	v_mov_b32_e32 v16, v169
	v_add_u32_e32 v20, 0x160000, v148
	v_pk_mul_f32 v[14:15], v[14:15], v[16:17] op_sel_hi:[1,0]
	v_pk_mul_f32 v[12:13], v[12:13], v[16:17] op_sel_hi:[1,0]
	v_pk_mul_f32 v[10:11], v[10:11], v[16:17] op_sel_hi:[1,0]
	v_pk_mul_f32 v[8:9], v[8:9], v[16:17] op_sel_hi:[1,0]
	v_pk_mul_f32 v[6:7], v[6:7], v[16:17] op_sel_hi:[1,0]
	v_pk_mul_f32 v[4:5], v[4:5], v[16:17] op_sel_hi:[1,0]
	v_pk_mul_f32 v[18:19], v[2:3], v[16:17] op_sel_hi:[1,0]
	v_pk_mul_f32 v[16:17], v[0:1], v[16:17] op_sel_hi:[1,0]
	v_cvt_pk_bf16_f32 v0, v12, v13
	v_cvt_pk_bf16_f32 v1, v14, v15
	v_cvt_pk_bf16_f32 v2, v8, v9
	v_cvt_pk_bf16_f32 v3, v10, v11
	buffer_store_dwordx4 v[0:3], v20, s[4:7], 0 offen sc1
	s_nop 1
	v_cvt_pk_bf16_f32 v0, v4, v5
	v_cvt_pk_bf16_f32 v1, v6, v7
	v_cvt_pk_bf16_f32 v2, v16, v17
	v_cvt_pk_bf16_f32 v3, v18, v19
	buffer_store_dwordx4 v[0:3], v20, s[4:7], 0 offen offset:256 sc1
	s_mov_b64 s[6:7], -1
	s_cbranch_vccnz .LBB0_154
	s_andn2_b64 vcc, exec, s[36:37]
	s_cbranch_vccnz .LBB0_153
	s_barrier
	s_branch .LBB0_153

.LBB0_361:
	s_add_u32 s16, s48, s38
	s_addc_u32 s17, s49, s39
	s_add_u32 s16, s16, 0x5800100
	s_addc_u32 s17, s17, 0
	s_add_u32 s28, s50, s38
	s_addc_u32 s29, s51, s39
	s_add_i32 s53, 0, 0x10000
	s_cmpk_eq_i32 s38, 0x700
	s_cselect_b32 s41, s37, s17
	s_cselect_b32 s40, s36, s16
	s_cselect_b32 s17, s35, s29
	s_cselect_b32 s16, s34, s28
	s_add_i32 s54, 0, 0x14000
	v_add_u32_e32 v154, s53, v140
	v_add_u32_e32 v158, s54, v140
	ds_read_b128 v[142:145], v154
	ds_read_b128 v[146:149], v154 offset:1024
	ds_read_b128 v[150:153], v154 offset:2048
	ds_read_b128 v[154:157], v154 offset:3072
	ds_read_b128 v[162:165], v158
	ds_read_b128 v[166:169], v158 offset:1024
	ds_read_b128 v[170:173], v158 offset:2048
	ds_read_b128 v[174:177], v158 offset:3072
	v_lshl_add_u64 v[158:159], v[134:135], 0, s[38:39]
	s_add_i32 m0, s27, 0xc000
	ds_read_b128 v[178:181], v141
	ds_read_b128 v[182:185], v141 offset:1024
	ds_read_b128 v[186:189], v141 offset:2048
	ds_read_b128 v[190:193], v141 offset:3072
	ds_read_b128 v[194:197], v141 offset:4096
	ds_read_b128 v[198:201], v141 offset:5120
	ds_read_b128 v[202:205], v141 offset:6144
	ds_read_b128 v[206:209], v141 offset:7168
	global_load_lds_dwordx4 v[158:159], off
	v_lshl_add_u64 v[158:159], v[136:137], 0, s[38:39]
	s_add_i32 m0, s27, 0xe000
	s_nop 0
	global_load_lds_dwordx4 v[158:159], off
	s_waitcnt vmcnt(8)
	s_waitcnt lgkmcnt(0)
	s_barrier
	s_setprio 1
	s_waitcnt lgkmcnt(0)
	v_mfma_f32_16x16x32_bf16 v[124:127], v[142:145], v[178:181], v[124:127]
	v_mfma_f32_16x16x32_bf16 v[120:123], v[150:153], v[178:181], v[120:123]
	v_mfma_f32_16x16x32_bf16 v[108:111], v[142:145], v[186:189], v[108:111]
	v_mfma_f32_16x16x32_bf16 v[104:107], v[150:153], v[186:189], v[104:107]
	v_mfma_f32_16x16x32_bf16 v[92:95], v[142:145], v[194:197], v[92:95]
	v_mfma_f32_16x16x32_bf16 v[88:91], v[150:153], v[194:197], v[88:91]
	v_mfma_f32_16x16x32_bf16 v[76:79], v[142:145], v[202:205], v[76:79]
	v_mfma_f32_16x16x32_bf16 v[72:75], v[150:153], v[202:205], v[72:75]
	v_mfma_f32_16x16x32_bf16 v[124:127], v[146:149], v[182:185], v[124:127]
	v_mfma_f32_16x16x32_bf16 v[120:123], v[154:157], v[182:185], v[120:123]
	v_mfma_f32_16x16x32_bf16 v[108:111], v[146:149], v[190:193], v[108:111]
	v_mfma_f32_16x16x32_bf16 v[104:107], v[154:157], v[190:193], v[104:107]
	v_mfma_f32_16x16x32_bf16 v[92:95], v[146:149], v[198:201], v[92:95]
	v_mfma_f32_16x16x32_bf16 v[88:91], v[154:157], v[198:201], v[88:91]
	v_mfma_f32_16x16x32_bf16 v[76:79], v[146:149], v[206:209], v[76:79]
	v_mfma_f32_16x16x32_bf16 v[72:75], v[154:157], v[206:209], v[72:75]
	s_setprio 0
	s_setprio 1
	v_mfma_f32_16x16x32_bf16 v[116:119], v[162:165], v[178:181], v[116:119]
	v_mfma_f32_16x16x32_bf16 v[112:115], v[170:173], v[178:181], v[112:115]
	v_mfma_f32_16x16x32_bf16 v[100:103], v[162:165], v[186:189], v[100:103]
	v_mfma_f32_16x16x32_bf16 v[96:99], v[170:173], v[186:189], v[96:99]
	v_mfma_f32_16x16x32_bf16 v[84:87], v[162:165], v[194:197], v[84:87]
	v_mfma_f32_16x16x32_bf16 v[80:83], v[170:173], v[194:197], v[80:83]
	v_mfma_f32_16x16x32_bf16 v[68:71], v[162:165], v[202:205], v[68:71]
	v_mfma_f32_16x16x32_bf16 v[64:67], v[170:173], v[202:205], v[64:67]
	v_mfma_f32_16x16x32_bf16 v[116:119], v[166:169], v[182:185], v[116:119]
	v_mfma_f32_16x16x32_bf16 v[112:115], v[174:177], v[182:185], v[112:115]
	v_mfma_f32_16x16x32_bf16 v[100:103], v[166:169], v[190:193], v[100:103]
	v_mfma_f32_16x16x32_bf16 v[96:99], v[174:177], v[190:193], v[96:99]
	v_mfma_f32_16x16x32_bf16 v[84:87], v[166:169], v[198:201], v[84:87]
	v_mfma_f32_16x16x32_bf16 v[80:83], v[174:177], v[198:201], v[80:83]
	v_mfma_f32_16x16x32_bf16 v[68:71], v[166:169], v[206:209], v[68:71]
	v_mfma_f32_16x16x32_bf16 v[64:67], v[174:177], v[206:209], v[64:67]
	s_setprio 0
	s_barrier
	s_add_i32 s28, s53, s26
	v_lshl_add_u64 v[158:159], s[16:17], 0, v[160:161]
	s_mov_b32 m0, s28
	ds_read_b128 v[178:181], v141 offset:16384
	ds_read_b128 v[182:185], v141 offset:17408
	ds_read_b128 v[186:189], v141 offset:18432
	ds_read_b128 v[190:193], v141 offset:19456
	ds_read_b128 v[194:197], v141 offset:20480
	ds_read_b128 v[198:201], v141 offset:21504
	ds_read_b128 v[202:205], v141 offset:22528
	ds_read_b128 v[206:209], v141 offset:23552
	global_load_lds_dwordx4 v[158:159], off
	s_add_i32 m0, s28, 0x2000
	s_add_u32 s28, s16, 0x40000
	v_lshl_add_u64 v[210:211], s[16:17], 0, v[132:133]
	s_addc_u32 s29, s17, 0
	s_add_i32 s53, s54, s26
	global_load_lds_dwordx4 v[210:211], off
	v_lshl_add_u64 v[212:213], s[28:29], 0, v[160:161]
	s_mov_b32 m0, s53
	v_lshl_add_u64 v[214:215], s[40:41], 0, v[130:131]
	global_load_lds_dwordx4 v[212:213], off
	v_lshl_add_u64 v[212:213], s[28:29], 0, v[132:133]
	s_add_i32 m0, s53, 0x2000
	s_nop 0
	global_load_lds_dwordx4 v[212:213], off
	v_lshl_add_u64 v[212:213], s[40:41], 0, v[128:129]
	s_mov_b32 m0, s27
	s_nop 0
	global_load_lds_dwordx4 v[212:213], off
	s_mov_b32 m0, s42
	s_nop 0
	global_load_lds_dwordx4 v[214:215], off
	s_waitcnt vmcnt(8)
	s_waitcnt lgkmcnt(0)
	s_barrier
	s_setprio 1
	s_waitcnt lgkmcnt(0)
	v_mfma_f32_16x16x32_bf16 v[60:63], v[142:145], v[178:181], v[60:63]
	v_mfma_f32_16x16x32_bf16 v[56:59], v[150:153], v[178:181], v[56:59]
	v_mfma_f32_16x16x32_bf16 v[44:47], v[142:145], v[186:189], v[44:47]
	v_mfma_f32_16x16x32_bf16 v[40:43], v[150:153], v[186:189], v[40:43]
	v_mfma_f32_16x16x32_bf16 v[28:31], v[142:145], v[194:197], v[28:31]
	v_mfma_f32_16x16x32_bf16 v[24:27], v[150:153], v[194:197], v[24:27]
	v_mfma_f32_16x16x32_bf16 v[12:15], v[142:145], v[202:205], v[12:15]
	v_mfma_f32_16x16x32_bf16 v[8:11], v[150:153], v[202:205], v[8:11]
	v_mfma_f32_16x16x32_bf16 v[60:63], v[146:149], v[182:185], v[60:63]
	v_mfma_f32_16x16x32_bf16 v[56:59], v[154:157], v[182:185], v[56:59]
	v_mfma_f32_16x16x32_bf16 v[44:47], v[146:149], v[190:193], v[44:47]
	v_mfma_f32_16x16x32_bf16 v[40:43], v[154:157], v[190:193], v[40:43]
	v_mfma_f32_16x16x32_bf16 v[28:31], v[146:149], v[198:201], v[28:31]
	v_mfma_f32_16x16x32_bf16 v[24:27], v[154:157], v[198:201], v[24:27]
	v_mfma_f32_16x16x32_bf16 v[12:15], v[146:149], v[206:209], v[12:15]
	v_mfma_f32_16x16x32_bf16 v[8:11], v[154:157], v[206:209], v[8:11]
	s_setprio 0
	s_setprio 1
	v_mfma_f32_16x16x32_bf16 v[52:55], v[162:165], v[178:181], v[52:55]
	v_mfma_f32_16x16x32_bf16 v[48:51], v[170:173], v[178:181], v[48:51]
	v_mfma_f32_16x16x32_bf16 v[36:39], v[162:165], v[186:189], v[36:39]
	v_mfma_f32_16x16x32_bf16 v[32:35], v[170:173], v[186:189], v[32:35]
	v_mfma_f32_16x16x32_bf16 v[20:23], v[162:165], v[194:197], v[20:23]
	v_mfma_f32_16x16x32_bf16 v[16:19], v[170:173], v[194:197], v[16:19]
	v_mfma_f32_16x16x32_bf16 v[4:7], v[162:165], v[202:205], v[4:7]
	v_mfma_f32_16x16x32_bf16 v[0:3], v[170:173], v[202:205], v[0:3]
	v_mfma_f32_16x16x32_bf16 v[52:55], v[166:169], v[182:185], v[52:55]
	v_mfma_f32_16x16x32_bf16 v[48:51], v[174:177], v[182:185], v[48:51]
	v_mfma_f32_16x16x32_bf16 v[36:39], v[166:169], v[190:193], v[36:39]
	v_mfma_f32_16x16x32_bf16 v[32:35], v[174:177], v[190:193], v[32:35]
	v_mfma_f32_16x16x32_bf16 v[20:23], v[166:169], v[198:201], v[20:23]
	v_mfma_f32_16x16x32_bf16 v[16:19], v[174:177], v[198:201], v[16:19]
	v_mfma_f32_16x16x32_bf16 v[4:7], v[166:169], v[206:209], v[4:7]
	v_mfma_f32_16x16x32_bf16 v[0:3], v[174:177], v[206:209], v[0:3]
	s_setprio 0
	s_barrier
	s_add_i32 s53, 0, 0x18000
	s_add_i32 s54, 0, 0x1c000
	v_add_u32_e32 v154, s53, v140
	v_add_u32_e32 v174, s54, v140
	ds_read_b128 v[142:145], v154
	ds_read_b128 v[146:149], v154 offset:1024
	ds_read_b128 v[150:153], v154 offset:2048
	ds_read_b128 v[154:157], v154 offset:3072
	ds_read_b128 v[162:165], v174
	ds_read_b128 v[166:169], v174 offset:1024
	ds_read_b128 v[170:173], v174 offset:2048
	ds_read_b128 v[174:177], v174 offset:3072
	s_add_u32 s28, s40, 0x40000
	s_addc_u32 s29, s41, 0
	s_mov_b32 m0, s43
	v_lshl_add_u64 v[216:217], s[28:29], 0, v[128:129]
	ds_read_b128 v[178:181], v141 offset:32768
	ds_read_b128 v[182:185], v141 offset:33792
	ds_read_b128 v[186:189], v141 offset:34816
	ds_read_b128 v[190:193], v141 offset:35840
	ds_read_b128 v[194:197], v141 offset:36864
	ds_read_b128 v[198:201], v141 offset:37888
	ds_read_b128 v[202:205], v141 offset:38912
	ds_read_b128 v[206:209], v141 offset:39936
	global_load_lds_dwordx4 v[216:217], off
	v_lshl_add_u64 v[216:217], s[28:29], 0, v[130:131]
	s_mov_b32 m0, s44
	s_nop 0
	global_load_lds_dwordx4 v[216:217], off
	s_waitcnt vmcnt(8)
	s_waitcnt lgkmcnt(0)
	s_barrier
	s_setprio 1
	s_waitcnt lgkmcnt(0)
	v_mfma_f32_16x16x32_bf16 v[124:127], v[142:145], v[178:181], v[124:127]
	v_mfma_f32_16x16x32_bf16 v[120:123], v[150:153], v[178:181], v[120:123]
	v_mfma_f32_16x16x32_bf16 v[108:111], v[142:145], v[186:189], v[108:111]
	v_mfma_f32_16x16x32_bf16 v[104:107], v[150:153], v[186:189], v[104:107]
	v_mfma_f32_16x16x32_bf16 v[92:95], v[142:145], v[194:197], v[92:95]
	v_mfma_f32_16x16x32_bf16 v[88:91], v[150:153], v[194:197], v[88:91]
	v_mfma_f32_16x16x32_bf16 v[76:79], v[142:145], v[202:205], v[76:79]
	v_mfma_f32_16x16x32_bf16 v[72:75], v[150:153], v[202:205], v[72:75]
	v_mfma_f32_16x16x32_bf16 v[124:127], v[146:149], v[182:185], v[124:127]
	v_mfma_f32_16x16x32_bf16 v[120:123], v[154:157], v[182:185], v[120:123]
	v_mfma_f32_16x16x32_bf16 v[108:111], v[146:149], v[190:193], v[108:111]
	v_mfma_f32_16x16x32_bf16 v[104:107], v[154:157], v[190:193], v[104:107]
	v_mfma_f32_16x16x32_bf16 v[92:95], v[146:149], v[198:201], v[92:95]
	v_mfma_f32_16x16x32_bf16 v[88:91], v[154:157], v[198:201], v[88:91]
	v_mfma_f32_16x16x32_bf16 v[76:79], v[146:149], v[206:209], v[76:79]
	v_mfma_f32_16x16x32_bf16 v[72:75], v[154:157], v[206:209], v[72:75]
	s_setprio 0
	s_setprio 1
	v_mfma_f32_16x16x32_bf16 v[116:119], v[162:165], v[178:181], v[116:119]
	v_mfma_f32_16x16x32_bf16 v[112:115], v[170:173], v[178:181], v[112:115]
	v_mfma_f32_16x16x32_bf16 v[100:103], v[162:165], v[186:189], v[100:103]
	v_mfma_f32_16x16x32_bf16 v[96:99], v[170:173], v[186:189], v[96:99]
	v_mfma_f32_16x16x32_bf16 v[84:87], v[162:165], v[194:197], v[84:87]
	v_mfma_f32_16x16x32_bf16 v[80:83], v[170:173], v[194:197], v[80:83]
	v_mfma_f32_16x16x32_bf16 v[68:71], v[162:165], v[202:205], v[68:71]
	v_mfma_f32_16x16x32_bf16 v[64:67], v[170:173], v[202:205], v[64:67]
	v_mfma_f32_16x16x32_bf16 v[116:119], v[166:169], v[182:185], v[116:119]
	v_mfma_f32_16x16x32_bf16 v[112:115], v[174:177], v[182:185], v[112:115]
	v_mfma_f32_16x16x32_bf16 v[100:103], v[166:169], v[190:193], v[100:103]
	v_mfma_f32_16x16x32_bf16 v[96:99], v[174:177], v[190:193], v[96:99]
	v_mfma_f32_16x16x32_bf16 v[84:87], v[166:169], v[198:201], v[84:87]
	v_mfma_f32_16x16x32_bf16 v[80:83], v[174:177], v[198:201], v[80:83]
	v_mfma_f32_16x16x32_bf16 v[68:71], v[166:169], v[206:209], v[68:71]
	v_mfma_f32_16x16x32_bf16 v[64:67], v[174:177], v[206:209], v[64:67]
	s_setprio 0
	s_barrier
	s_add_i32 s28, s53, s26
	v_lshl_add_u64 v[158:159], v[158:159], 0, s[76:77]
	s_mov_b32 m0, s28
	ds_read_b128 v[178:181], v141 offset:49152
	ds_read_b128 v[182:185], v141 offset:50176
	ds_read_b128 v[186:189], v141 offset:51200
	ds_read_b128 v[190:193], v141 offset:52224
	ds_read_b128 v[194:197], v141 offset:53248
	ds_read_b128 v[198:201], v141 offset:54272
	ds_read_b128 v[202:205], v141 offset:55296
	ds_read_b128 v[206:209], v141 offset:56320
	global_load_lds_dwordx4 v[158:159], off
	s_add_i32 m0, s28, 0x2000
	s_add_u32 s16, s16, 0x40080
	v_lshl_add_u64 v[158:159], v[210:211], 0, s[76:77]
	s_addc_u32 s17, s17, 0
	s_add_i32 s28, s54, s26
	global_load_lds_dwordx4 v[158:159], off
	v_lshl_add_u64 v[158:159], s[16:17], 0, v[160:161]
	s_mov_b32 m0, s28
	s_nop 0
	global_load_lds_dwordx4 v[158:159], off
	v_lshl_add_u64 v[158:159], s[16:17], 0, v[132:133]
	s_add_i32 m0, s28, 0x2000
	s_nop 0
	global_load_lds_dwordx4 v[158:159], off
	v_lshl_add_u64 v[158:159], v[212:213], 0, s[76:77]
	s_mov_b32 m0, s46
	s_nop 0
	global_load_lds_dwordx4 v[158:159], off
	v_lshl_add_u64 v[158:159], v[214:215], 0, s[76:77]
	s_mov_b32 m0, s47
	s_nop 0
	global_load_lds_dwordx4 v[158:159], off
	s_waitcnt vmcnt(8)
	s_waitcnt lgkmcnt(0)
	s_barrier
	s_setprio 1
	s_waitcnt lgkmcnt(0)
	v_mfma_f32_16x16x32_bf16 v[60:63], v[142:145], v[178:181], v[60:63]
	v_mfma_f32_16x16x32_bf16 v[56:59], v[150:153], v[178:181], v[56:59]
	v_mfma_f32_16x16x32_bf16 v[44:47], v[142:145], v[186:189], v[44:47]
	v_mfma_f32_16x16x32_bf16 v[40:43], v[150:153], v[186:189], v[40:43]
	v_mfma_f32_16x16x32_bf16 v[28:31], v[142:145], v[194:197], v[28:31]
	v_mfma_f32_16x16x32_bf16 v[24:27], v[150:153], v[194:197], v[24:27]
	v_mfma_f32_16x16x32_bf16 v[12:15], v[142:145], v[202:205], v[12:15]
	v_mfma_f32_16x16x32_bf16 v[8:11], v[150:153], v[202:205], v[8:11]
	v_mfma_f32_16x16x32_bf16 v[60:63], v[146:149], v[182:185], v[60:63]
	v_mfma_f32_16x16x32_bf16 v[56:59], v[154:157], v[182:185], v[56:59]
	v_mfma_f32_16x16x32_bf16 v[44:47], v[146:149], v[190:193], v[44:47]
	v_mfma_f32_16x16x32_bf16 v[40:43], v[154:157], v[190:193], v[40:43]
	v_mfma_f32_16x16x32_bf16 v[28:31], v[146:149], v[198:201], v[28:31]
	v_mfma_f32_16x16x32_bf16 v[24:27], v[154:157], v[198:201], v[24:27]
	v_mfma_f32_16x16x32_bf16 v[12:15], v[146:149], v[206:209], v[12:15]
	v_mfma_f32_16x16x32_bf16 v[8:11], v[154:157], v[206:209], v[8:11]
	s_setprio 0
	s_setprio 1
	v_mfma_f32_16x16x32_bf16 v[52:55], v[162:165], v[178:181], v[52:55]
	v_mfma_f32_16x16x32_bf16 v[48:51], v[170:173], v[178:181], v[48:51]
	v_mfma_f32_16x16x32_bf16 v[36:39], v[162:165], v[186:189], v[36:39]
	v_mfma_f32_16x16x32_bf16 v[32:35], v[170:173], v[186:189], v[32:35]
	v_mfma_f32_16x16x32_bf16 v[20:23], v[162:165], v[194:197], v[20:23]
	v_mfma_f32_16x16x32_bf16 v[16:19], v[170:173], v[194:197], v[16:19]
	v_mfma_f32_16x16x32_bf16 v[4:7], v[162:165], v[202:205], v[4:7]
	v_mfma_f32_16x16x32_bf16 v[0:3], v[170:173], v[202:205], v[0:3]
	v_mfma_f32_16x16x32_bf16 v[52:55], v[166:169], v[182:185], v[52:55]
	v_mfma_f32_16x16x32_bf16 v[48:51], v[174:177], v[182:185], v[48:51]
	v_mfma_f32_16x16x32_bf16 v[36:39], v[166:169], v[190:193], v[36:39]
	v_mfma_f32_16x16x32_bf16 v[32:35], v[174:177], v[190:193], v[32:35]
	v_mfma_f32_16x16x32_bf16 v[20:23], v[166:169], v[198:201], v[20:23]
	v_mfma_f32_16x16x32_bf16 v[16:19], v[174:177], v[198:201], v[16:19]
	v_mfma_f32_16x16x32_bf16 v[4:7], v[166:169], v[206:209], v[4:7]
	v_mfma_f32_16x16x32_bf16 v[0:3], v[174:177], v[206:209], v[0:3]
	s_setprio 0
	s_barrier
	s_add_i32 s52, s52, 2
	s_add_u32 s38, s38, 0x100
	s_addc_u32 s39, s39, 0
	s_cmp_gt_u32 s52, 13
	s_cbranch_scc0 .LBB0_361
	s_lshl_b32 s16, s45, 6
	s_lshl_b32 s17, s25, 9
	s_or_b32 s16, s16, s17
	v_lshl_add_u32 v130, s68, 8, v139
	v_or_b32_e32 v133, s16, v138
	v_readlane_b32 s16, v253, 54
	v_ashrrev_i32_e32 v131, 31, v130
	v_readlane_b32 s17, v253, 55
	s_mov_b32 s90, s82
	s_mov_b32 s91, s83
	v_lshl_add_u64 v[128:129], v[130:131], 2, s[16:17]
	global_load_dword v132, v[128:129], off
	global_load_dword v163, v[128:129], off offset:64
	global_load_dword v164, v[128:129], off offset:128
	global_load_dword v165, v[128:129], off offset:192
	global_load_dword v166, v[128:129], off offset:512
	global_load_dword v167, v[128:129], off offset:576
	global_load_dword v168, v[128:129], off offset:640
	global_load_dword v169, v[128:129], off offset:704
	v_lshl_or_b32 v130, v130, 13, v133
	s_cmpk_lt_u32 s24, 0x100
	s_waitcnt vmcnt(0)
	v_pk_mul_f32 v[126:127], v[126:127], v[132:133] op_sel_hi:[1,0]
	v_pk_mul_f32 v[124:125], v[124:125], v[132:133] op_sel_hi:[1,0]
	v_pk_mul_f32 v[134:135], v[122:123], v[132:133] op_sel_hi:[1,0]
	v_pk_mul_f32 v[122:123], v[120:121], v[132:133] op_sel_hi:[1,0]
	v_cvt_pk_bf16_f32 v120, v124, v125
	v_cvt_pk_bf16_f32 v121, v126, v127
	v_pk_mul_f32 v[118:119], v[118:119], v[132:133] op_sel_hi:[1,0]
	v_cvt_pk_bf16_f32 v122, v122, v123
	v_cvt_pk_bf16_f32 v123, v134, v135
	buffer_store_dwordx4 v[120:123], v130, s[88:91], 0 offen sc1
	v_pk_mul_f32 v[116:117], v[116:117], v[132:133] op_sel_hi:[1,0]
	s_nop 0
	v_pk_mul_f32 v[120:121], v[114:115], v[132:133] op_sel_hi:[1,0]
	v_pk_mul_f32 v[114:115], v[112:113], v[132:133] op_sel_hi:[1,0]
	v_cvt_pk_bf16_f32 v112, v116, v117
	v_cvt_pk_bf16_f32 v113, v118, v119
	s_nop 0
	v_cvt_pk_bf16_f32 v114, v114, v115
	v_cvt_pk_bf16_f32 v115, v120, v121
	buffer_store_dwordx4 v[112:115], v130, s[88:91], 0 offen offset:256 sc1
	s_nop 1
	v_mov_b32_e32 v112, v163
	s_nop 0
	v_add_u32_e32 v113, 0x20000, v130
	v_pk_mul_f32 v[110:111], v[110:111], v[112:113] op_sel_hi:[1,0]
	v_pk_mul_f32 v[108:109], v[108:109], v[112:113] op_sel_hi:[1,0]
	v_pk_mul_f32 v[114:115], v[106:107], v[112:113] op_sel_hi:[1,0]
	v_pk_mul_f32 v[106:107], v[104:105], v[112:113] op_sel_hi:[1,0]
	v_cvt_pk_bf16_f32 v104, v108, v109
	v_cvt_pk_bf16_f32 v105, v110, v111
	v_pk_mul_f32 v[102:103], v[102:103], v[112:113] op_sel_hi:[1,0]
	v_cvt_pk_bf16_f32 v106, v106, v107
	v_cvt_pk_bf16_f32 v107, v114, v115
	buffer_store_dwordx4 v[104:107], v113, s[88:91], 0 offen sc1
	v_pk_mul_f32 v[100:101], v[100:101], v[112:113] op_sel_hi:[1,0]
	s_nop 0
	v_pk_mul_f32 v[104:105], v[98:99], v[112:113] op_sel_hi:[1,0]
	v_pk_mul_f32 v[98:99], v[96:97], v[112:113] op_sel_hi:[1,0]
	v_cvt_pk_bf16_f32 v96, v100, v101
	v_cvt_pk_bf16_f32 v97, v102, v103
	s_nop 0
	v_cvt_pk_bf16_f32 v98, v98, v99
	v_cvt_pk_bf16_f32 v99, v104, v105
	buffer_store_dwordx4 v[96:99], v113, s[88:91], 0 offen offset:256 sc1
	s_nop 1
	v_mov_b32_e32 v96, v164
	s_nop 0
	v_add_u32_e32 v97, 0x40000, v130
	v_pk_mul_f32 v[94:95], v[94:95], v[96:97] op_sel_hi:[1,0]
	v_pk_mul_f32 v[92:93], v[92:93], v[96:97] op_sel_hi:[1,0]
	v_pk_mul_f32 v[98:99], v[90:91], v[96:97] op_sel_hi:[1,0]
	v_pk_mul_f32 v[90:91], v[88:89], v[96:97] op_sel_hi:[1,0]
	v_cvt_pk_bf16_f32 v88, v92, v93
	v_cvt_pk_bf16_f32 v89, v94, v95
	v_pk_mul_f32 v[86:87], v[86:87], v[96:97] op_sel_hi:[1,0]
	v_cvt_pk_bf16_f32 v90, v90, v91
	v_cvt_pk_bf16_f32 v91, v98, v99
	buffer_store_dwordx4 v[88:91], v97, s[88:91], 0 offen sc1
	v_pk_mul_f32 v[84:85], v[84:85], v[96:97] op_sel_hi:[1,0]
	s_nop 0
	v_pk_mul_f32 v[88:89], v[82:83], v[96:97] op_sel_hi:[1,0]
	v_pk_mul_f32 v[82:83], v[80:81], v[96:97] op_sel_hi:[1,0]
	v_cvt_pk_bf16_f32 v80, v84, v85
	v_cvt_pk_bf16_f32 v81, v86, v87
	s_nop 0
	v_cvt_pk_bf16_f32 v82, v82, v83
	v_cvt_pk_bf16_f32 v83, v88, v89
	buffer_store_dwordx4 v[80:83], v97, s[88:91], 0 offen offset:256 sc1
	s_nop 1
	v_mov_b32_e32 v80, v165
	s_nop 0
	v_add_u32_e32 v81, 0x60000, v130
	v_pk_mul_f32 v[78:79], v[78:79], v[80:81] op_sel_hi:[1,0]
	v_pk_mul_f32 v[76:77], v[76:77], v[80:81] op_sel_hi:[1,0]
	v_pk_mul_f32 v[82:83], v[74:75], v[80:81] op_sel_hi:[1,0]
	v_pk_mul_f32 v[74:75], v[72:73], v[80:81] op_sel_hi:[1,0]
	v_cvt_pk_bf16_f32 v72, v76, v77
	v_cvt_pk_bf16_f32 v73, v78, v79
	v_pk_mul_f32 v[70:71], v[70:71], v[80:81] op_sel_hi:[1,0]
	v_cvt_pk_bf16_f32 v74, v74, v75
	v_cvt_pk_bf16_f32 v75, v82, v83
	buffer_store_dwordx4 v[72:75], v81, s[88:91], 0 offen sc1
	v_pk_mul_f32 v[68:69], v[68:69], v[80:81] op_sel_hi:[1,0]
	s_nop 0
	v_pk_mul_f32 v[72:73], v[66:67], v[80:81] op_sel_hi:[1,0]
	v_pk_mul_f32 v[66:67], v[64:65], v[80:81] op_sel_hi:[1,0]
	v_cvt_pk_bf16_f32 v64, v68, v69
	v_cvt_pk_bf16_f32 v65, v70, v71
	s_nop 0
	v_cvt_pk_bf16_f32 v66, v66, v67
	v_cvt_pk_bf16_f32 v67, v72, v73
	buffer_store_dwordx4 v[64:67], v81, s[88:91], 0 offen offset:256 sc1
	s_nop 1
	v_mov_b32_e32 v64, v166
	s_nop 0
	v_add_u32_e32 v65, 0x100000, v130
	v_pk_mul_f32 v[62:63], v[62:63], v[64:65] op_sel_hi:[1,0]
	v_pk_mul_f32 v[60:61], v[60:61], v[64:65] op_sel_hi:[1,0]
	v_pk_mul_f32 v[66:67], v[58:59], v[64:65] op_sel_hi:[1,0]
	v_pk_mul_f32 v[58:59], v[56:57], v[64:65] op_sel_hi:[1,0]
	v_cvt_pk_bf16_f32 v56, v60, v61
	v_cvt_pk_bf16_f32 v57, v62, v63
	v_pk_mul_f32 v[54:55], v[54:55], v[64:65] op_sel_hi:[1,0]
	v_cvt_pk_bf16_f32 v58, v58, v59
	v_cvt_pk_bf16_f32 v59, v66, v67
	buffer_store_dwordx4 v[56:59], v65, s[88:91], 0 offen sc1
	v_pk_mul_f32 v[52:53], v[52:53], v[64:65] op_sel_hi:[1,0]
	s_nop 0
	v_pk_mul_f32 v[56:57], v[50:51], v[64:65] op_sel_hi:[1,0]
	v_pk_mul_f32 v[50:51], v[48:49], v[64:65] op_sel_hi:[1,0]
	v_cvt_pk_bf16_f32 v48, v52, v53
	v_cvt_pk_bf16_f32 v49, v54, v55
	s_nop 0
	v_cvt_pk_bf16_f32 v50, v50, v51
	v_cvt_pk_bf16_f32 v51, v56, v57
	buffer_store_dwordx4 v[48:51], v65, s[88:91], 0 offen offset:256 sc1
	s_nop 1
	v_mov_b32_e32 v48, v167
	s_nop 0
	v_add_u32_e32 v49, 0x120000, v130
	v_pk_mul_f32 v[46:47], v[46:47], v[48:49] op_sel_hi:[1,0]
	v_pk_mul_f32 v[44:45], v[44:45], v[48:49] op_sel_hi:[1,0]
	v_pk_mul_f32 v[50:51], v[42:43], v[48:49] op_sel_hi:[1,0]
	v_pk_mul_f32 v[42:43], v[40:41], v[48:49] op_sel_hi:[1,0]
	v_cvt_pk_bf16_f32 v40, v44, v45
	v_cvt_pk_bf16_f32 v41, v46, v47
	v_pk_mul_f32 v[38:39], v[38:39], v[48:49] op_sel_hi:[1,0]
	v_cvt_pk_bf16_f32 v42, v42, v43
	v_cvt_pk_bf16_f32 v43, v50, v51
	buffer_store_dwordx4 v[40:43], v49, s[88:91], 0 offen sc1
	v_pk_mul_f32 v[36:37], v[36:37], v[48:49] op_sel_hi:[1,0]
	s_nop 0
	v_pk_mul_f32 v[40:41], v[34:35], v[48:49] op_sel_hi:[1,0]
	v_pk_mul_f32 v[34:35], v[32:33], v[48:49] op_sel_hi:[1,0]
	v_cvt_pk_bf16_f32 v32, v36, v37
	v_cvt_pk_bf16_f32 v33, v38, v39
	s_nop 0
	v_cvt_pk_bf16_f32 v34, v34, v35
	v_cvt_pk_bf16_f32 v35, v40, v41
	buffer_store_dwordx4 v[32:35], v49, s[88:91], 0 offen offset:256 sc1
	s_nop 1
	v_mov_b32_e32 v32, v168
	s_nop 0
	v_add_u32_e32 v33, 0x140000, v130
	v_pk_mul_f32 v[30:31], v[30:31], v[32:33] op_sel_hi:[1,0]
	v_pk_mul_f32 v[28:29], v[28:29], v[32:33] op_sel_hi:[1,0]
	v_pk_mul_f32 v[34:35], v[26:27], v[32:33] op_sel_hi:[1,0]
	v_pk_mul_f32 v[26:27], v[24:25], v[32:33] op_sel_hi:[1,0]
	v_cvt_pk_bf16_f32 v24, v28, v29
	v_cvt_pk_bf16_f32 v25, v30, v31
	v_pk_mul_f32 v[22:23], v[22:23], v[32:33] op_sel_hi:[1,0]
	v_cvt_pk_bf16_f32 v26, v26, v27
	v_cvt_pk_bf16_f32 v27, v34, v35
	buffer_store_dwordx4 v[24:27], v33, s[88:91], 0 offen sc1
	v_pk_mul_f32 v[20:21], v[20:21], v[32:33] op_sel_hi:[1,0]
	s_nop 0
	v_pk_mul_f32 v[24:25], v[18:19], v[32:33] op_sel_hi:[1,0]
	v_pk_mul_f32 v[18:19], v[16:17], v[32:33] op_sel_hi:[1,0]
	v_cvt_pk_bf16_f32 v16, v20, v21
	v_cvt_pk_bf16_f32 v17, v22, v23
	s_nop 0
	v_cvt_pk_bf16_f32 v18, v18, v19
	v_cvt_pk_bf16_f32 v19, v24, v25
	buffer_store_dwordx4 v[16:19], v33, s[88:91], 0 offen offset:256 sc1
	s_nop 1
	v_mov_b32_e32 v16, v169
	s_nop 0
	v_add_u32_e32 v17, 0x160000, v130
	v_pk_mul_f32 v[14:15], v[14:15], v[16:17] op_sel_hi:[1,0]
	v_pk_mul_f32 v[12:13], v[12:13], v[16:17] op_sel_hi:[1,0]
	v_pk_mul_f32 v[18:19], v[10:11], v[16:17] op_sel_hi:[1,0]
	v_pk_mul_f32 v[10:11], v[8:9], v[16:17] op_sel_hi:[1,0]
	v_cvt_pk_bf16_f32 v8, v12, v13
	v_cvt_pk_bf16_f32 v9, v14, v15
	v_pk_mul_f32 v[6:7], v[6:7], v[16:17] op_sel_hi:[1,0]
	v_cvt_pk_bf16_f32 v10, v10, v11
	v_cvt_pk_bf16_f32 v11, v18, v19
	buffer_store_dwordx4 v[8:11], v17, s[88:91], 0 offen sc1
	v_pk_mul_f32 v[4:5], v[4:5], v[16:17] op_sel_hi:[1,0]
	s_nop 0
	v_pk_mul_f32 v[8:9], v[2:3], v[16:17] op_sel_hi:[1,0]
	v_pk_mul_f32 v[2:3], v[0:1], v[16:17] op_sel_hi:[1,0]
	v_cvt_pk_bf16_f32 v0, v4, v5
	v_cvt_pk_bf16_f32 v1, v6, v7
	s_nop 0
	v_cvt_pk_bf16_f32 v2, v2, v3
	v_cvt_pk_bf16_f32 v3, v8, v9
	buffer_store_dwordx4 v[0:3], v17, s[88:91], 0 offen offset:256 sc1
	s_waitcnt vmcnt(0)
	s_cbranch_scc0 .LBB0_364
	s_barrier
